# attention: canonicalizing self-max instructions removed from the row-max reductions; relative-bias table load no longer waited on at unit start
# baseline (speedup 1.0000x reference)
; #define ATT_LOAD(j) do { _Pragma("unroll") for (int i = 0; i < 2; ++i) { const int id = tid + 512 * i; \
;             kreg[i] = *(const u32x4*)(kbase + (size_t)((j) * 64 + (id >> 4)) * LDP + (id & 15) * 8); \
;             vreg[i] = *(const u32x4*)(vbase + (size_t)(id >> 3) * TP + (j) * 64 + (id & 7) * 8); } } while (0)
; #define ATT_STORE(buf) do { _Pragma("unroll") for (int i = 0; i < 2; ++i) { const int id = tid + 512 * i; \
;             *(LAS u32x4*)(lds + (buf) * KBYTES + (id >> 4) * KPITCH + (id & 15) * 16) = kreg[i]; \
;             *(LAS u32x4*)(lds + 2 * KBYTES + (buf) * VBYTES + (id >> 3) * VPITCH + (id & 7) * 16) = vreg[i]; } } while (0)
; __device__ __forceinline__ void attn_phase(LAS unsigned char* lds, bf16_t* p5, const bf16_t* vt, const float* relb, const float* dalam, const float* subln, float lam_init, int ocol) {
;     ...
;     for (int r = 0;; ++r) {
;         const int idx = (r & 1) ? r * G + (G - 1 - c) : r * G + c;
;         if (r * G >= 33 * 32) break;
;         if (idx >= 33 * 32) continue;
;         const int qt = 32 - idx / 32, bh = idx & 31, b = bh >> 3, h = bh & 7;
;         const int njt = (2 * qt + 2) < 65 ? (2 * qt + 2) : 65;
;         const int qrow0 = qt * 128 + rgi * 32;
;         __syncthreads();
;         if (tid < 128) { const int d = tid; int bk = d; if (d >= 16) { bk = 16 + (int)(logf((float)d * (1.0f / 16.0f)) * (16.0f / logf(8.0f))); if (bk > 31) bk = 31; } btab[d] = relb[bk * 8 + h] * LOG2E; }
;         const float bfar = relb[31 * 8 + h] * LOG2E;
;         bf16x8 qf[2][2];
; #pragma unroll
;         for (int rg = 0; rg < 2; ++rg) { const int q = qrow0 + 16 * rg + lq, qc = q < TP ? q : TP - 1;
; #pragma unroll
;             for (int s = 0; s < 2; ++s) qf[rg][s] = *(const bf16x8*)(p5 + ((size_t)b * TP + qc) * LDP + C_Q + h * 128 + cc * 64 + s * 32 + 8 * g4); }
;         f32x4 O[2][8]; float mrow[2], lrow[2];
; #pragma unroll
;         for (int rg = 0; rg < 2; ++rg) { mrow[rg] = -INFINITY; lrow[rg] = 0.f;
; #pragma unroll
;             for (int k = 0; k < 8; ++k) O[rg][k] = (f32x4){0.f, 0.f, 0.f, 0.f}; }
;         u32x4 kreg[2], vreg[2];
;         const bf16_t* kbase = p5 + (size_t)b * TP * LDP + C_K + h * 128; const bf16_t* vbase = vt + (size_t)bh * 128 * TP;
;     ...
;         ATT_LOAD(0); ATT_STORE(0); __syncthreads();
.LBB0_643:
	s_mul_i32 s19, s41, s64
	s_cmpk_gt_i32 s19, 0x41f
	s_mov_b32 s30, 5
	s_cbranch_scc1 .LBB0_790
	s_bitcmp0_b32 s41, 0
	v_readlane_b32 s24, v253, 18
	s_cselect_b32 s24, s2, s24
	s_add_i32 s19, s24, s19
	s_cmpk_gt_i32 s19, 0x41f
	s_mov_b32 s30, 7
	s_cbranch_scc1 .LBB0_790
	s_and_b32 s30, s19, 7
	s_barrier
	s_and_saveexec_b64 s[24:25], s[42:43]
	s_cbranch_execz .LBB0_647
	v_or_b32_e32 v2, s30, v179
	v_ashrrev_i32_e32 v3, 31, v2
	v_lshl_add_u64 v[2:3], v[2:3], 2, s[0:1]
	global_load_dword v246, v[2:3], off
.LBB0_647:
	s_or_b64 exec, exec, s[24:25]
	s_ashr_i32 s24, s19, 31
	s_lshr_b32 s24, s24, 27
	s_add_i32 s24, s19, s24
	s_ashr_i32 s34, s24, 5
	s_sub_i32 s31, 32, s34
	s_lshl_b32 s46, s31, 7
	s_add_i32 s46, s46, s40
	v_or_b32_e32 v168, s46, v141
	s_and_b32 s35, s19, 31
	s_bfe_u32 s19, s19, 0x20003
	v_min_i32_e32 v2, 0x103f, v168
	s_mul_i32 s24, s19, 0x1040
	s_mov_b32 s25, s69
	v_ashrrev_i32_e32 v3, 31, v2
	v_lshl_add_u64 v[2:3], v[2:3], 0, s[24:25]
	v_mov_b64_e32 v[4:5], s[4:5]
	v_mad_u64_u32 v[6:7], s[28:29], v2, s84, v[4:5]
	v_mad_i32_i24 v7, v3, s84, v7
	s_lshl_b32 s68, s30, 8
	v_or_b32_e32 v166, 16, v168
	v_lshl_add_u64 v[2:3], v[6:7], 0, s[68:69]
	v_min_i32_e32 v6, 0x103f, v166
	v_ashrrev_i32_e32 v7, 31, v6
	s_lshl_b32 s44, s30, 2
	v_lshl_add_u64 v[6:7], v[6:7], 0, s[24:25]
	s_mul_i32 s19, s19, 0x28a0000
	v_mad_u64_u32 v[4:5], s[28:29], v6, s84, v[4:5]
	s_add_u32 s19, s4, s19
	s_addc_u32 s29, s5, 0
	s_add_u32 s28, s19, s68
	s_addc_u32 s29, s29, 0
	v_mov_b32_e32 v161, v1
	v_mad_i32_i24 v5, v7, s84, v5
	v_lshl_add_u64 v[6:7], s[28:29], 0, v[160:161]
	s_mov_b64 s[28:29], 0x1800
	v_lshl_add_u64 v[4:5], v[4:5], 0, s[68:69]
	v_lshl_add_u64 v[170:171], v[6:7], 0, s[28:29]
	s_mul_i32 s68, s35, 0x104000
	v_lshl_add_u64 v[172:173], v[146:147], 0, s[68:69]
	v_lshl_add_u64 v[6:7], v[170:171], 0, v[148:149]
	global_load_dwordx4 v[20:23], v[6:7], off
	v_lshl_add_u64 v[36:37], v[172:173], 0, v[150:151]
	global_load_dwordx4 v[24:27], v[36:37], off
	v_lshl_add_u64 v[6:7], v[170:171], 0, v[152:153]
	global_load_dwordx4 v[28:31], v[6:7], off
	v_lshl_add_u64 v[38:39], v[172:173], 0, v[154:155]
	global_load_dwordx4 v[32:35], v[38:39], off
	s_mov_b32 s19, s69
	v_lshlrev_b32_e32 v0, 1, v140
	v_lshl_add_u64 v[2:3], v[2:3], 0, s[18:19]
	v_lshl_add_u64 v[2:3], v[2:3], 0, v[0:1]
	v_lshl_add_u64 v[4:5], v[4:5], 0, s[18:19]
	s_mov_b64 s[28:29], 0x1000
	s_movk_i32 s19, 0x1000
	v_lshl_add_u64 v[8:9], v[2:3], 0, s[28:29]
	v_add_co_u32_e32 v2, vcc, s19, v2
	v_mov_b32_e32 v6, s44
	s_nop 0
	v_addc_co_u32_e32 v3, vcc, 0, v3, vcc
	v_lshl_add_u64 v[12:13], v[4:5], 0, v[0:1]
	global_load_dword v44, v6, s[0:1] offset:992
	s_nop 0
	global_load_dwordx4 v[4:7], v[2:3], off
	s_nop 0
	global_load_dwordx4 v[8:11], v[8:9], off offset:64
	v_lshl_add_u64 v[2:3], v[12:13], 0, s[28:29]
	v_add_co_u32_e32 v12, vcc, s19, v12
	v_add_u32_e32 v100, v165, v182
	v_lshl_add_u64 v[40:41], v[170:171], 0, v[156:157]
	v_addc_co_u32_e32 v13, vcc, 0, v13, vcc
	v_add_u32_e32 v101, v174, v183
	v_add_u32_e32 v102, v165, v184
	v_add_u32_e32 v103, v174, v185
	v_lshl_add_u64 v[42:43], v[170:171], 0, v[158:159]
	global_load_dwordx4 v[12:15], v[12:13], off
	s_nop 0
	global_load_dwordx4 v[16:19], v[2:3], off offset:64
	s_cmp_lt_i32 s46, 0
	s_waitcnt vmcnt(8)
	ds_write_b128 v100, v[20:23]
	s_mov_b64 exec, s[42:43]
	v_mul_f32_e32 v246, 0x3fb8aa3b, v246
	ds_write_b32 v143, v246
	s_mov_b64 exec, -1
	s_waitcnt vmcnt(7)
	ds_write_b128 v101, v[24:27] offset:34816
	s_waitcnt vmcnt(6)
	ds_write_b128 v102, v[28:31]
	s_waitcnt vmcnt(5)
	ds_write_b128 v103, v[32:35] offset:34816
	s_waitcnt lgkmcnt(0)
	s_barrier
	global_load_dwordx4 v[20:23], v[40:41], off
	global_load_dwordx4 v[28:31], v[42:43], off
	global_load_dwordx4 v[24:27], v[36:37], off offset:128
	global_load_dwordx4 v[32:35], v[38:39], off offset:128
	s_waitcnt vmcnt(8)
	v_mul_f32_e32 v222, 0x3fb8aa3b, v44
	s_cbranch_scc1 .LBB0_665
	v_add_u32_e32 v0, v175, v186
	ds_read_b128 v[36:39], v0 offset:13056
	ds_read_b128 v[40:43], v0 offset:13120
	s_waitcnt vmcnt(7) lgkmcnt(1)
	v_mfma_f32_16x16x32_bf16 v[44:47], v[36:39], v[4:7], 0
	s_waitcnt vmcnt(5)
	v_mfma_f32_16x16x32_bf16 v[36:39], v[36:39], v[12:15], 0
	s_waitcnt lgkmcnt(0)
	v_mfma_f32_16x16x32_bf16 v[48:51], v[40:43], v[8:11], v[44:47]
	s_waitcnt vmcnt(4)
	v_mfma_f32_16x16x32_bf16 v[44:47], v[40:43], v[16:19], v[36:39]
	v_add_u32_e32 v2, v188, v140
	v_add_u32_e32 v0, 0x8800, v2
	ds_read2_b64 v[40:43], v0 offset1:4
	s_nop 0
	ds_read2_b64 v[36:39], v0 offset0:8 offset1:12
	v_sub_u32_e32 v0, v168, v189
	v_cmp_gt_u32_e32 vcc, s77, v0
	v_mov_b32_e32 v3, v222
	s_and_saveexec_b64 s[28:29], vcc
	v_lshl_add_u32 v3, v0, 2, 0
	v_add_u32_e32 v3, 0x11800, v3
	ds_read_b32 v3, v3
	s_or_b64 exec, exec, s[28:29]
	v_sub_u32_e32 v52, v168, v190
	v_cmp_gt_u32_e32 vcc, s77, v52
	v_mov_b32_e32 v53, v222
	s_and_saveexec_b64 s[28:29], vcc
	v_lshl_add_u32 v53, v52, 2, 0
	v_add_u32_e32 v53, 0x11800, v53
	ds_read_b32 v53, v53
	s_or_b64 exec, exec, s[28:29]
	v_sub_u32_e32 v54, v168, v191
	v_cmp_gt_u32_e32 vcc, s77, v54
	v_mov_b32_e32 v55, v222
	s_and_saveexec_b64 s[28:29], vcc
	v_lshl_add_u32 v55, v54, 2, 0
	v_add_u32_e32 v55, 0x11800, v55
	ds_read_b32 v55, v55
	s_or_b64 exec, exec, s[28:29]
	v_sub_u32_e32 v56, v168, v192
	v_cmp_gt_u32_e32 vcc, s77, v56
	v_mov_b32_e32 v57, v222
	s_and_saveexec_b64 s[28:29], vcc
	v_lshl_add_u32 v57, v56, 2, 0
	v_add_u32_e32 v57, 0x11800, v57
	ds_read_b32 v57, v57
	s_or_b64 exec, exec, s[28:29]
	s_waitcnt lgkmcnt(0)
; __device__ __forceinline__ void attn_phase(LAS unsigned char* lds, bf16_t* p5, const bf16_t* vt, const float* relb, const float* dalam, const float* subln, float lam_init, int ocol) {
;     ...
;                 for (int rg = 0; rg < 2; ++rg) {
;                     float rmax = -INFINITY, msafe, alpha;
;                     if (far) {
; #pragma unroll
;                         for (int kb = 0; kb < 4; ++kb)
; #pragma unroll
;                             for (int i = 0; i < 4; ++i) rmax = fmaxf(rmax, st[rg][kb][i]);
;                         rmax = rows4_max(rmax);
;                         const float mnew = fmaxf(mrow[rg], rmax * sc2 + bfar); msafe = mnew;
;                         alpha = __builtin_amdgcn_exp2f(mrow[rg] - msafe); mrow[rg] = mnew;
;                         const float off = bfar - msafe;
; #pragma unroll
;                         for (int kb = 0; kb < 4; ++kb)
; #pragma unroll
;                             for (int i = 0; i < 4; ++i) st[rg][kb][i] = __builtin_amdgcn_exp2f(st[rg][kb][i] * sc2 + off);
;                     } else {
;                         const int q = qrow0 + 16 * rg + lq;
; #pragma unroll
;                         for (int kb = 0; kb < 4; ++kb)
; #pragma unroll
;                             for (int i = 0; i < 4; ++i) { float v = st[rg][kb][i] * sc2;
;                                 const int kp = j * 64 + 16 * kb + 4 * g4 + i; const int dist = q - kp;
;                                 const float bv = (dist >= 0 && dist < 128) ? btab[dist] : bfar;
;                                 v = (kp >= PADT && dist >= 0) ? v + bv : -INFINITY;
;                                 st[rg][kb][i] = v; rmax = fmaxf(rmax, v); }
;                         rmax = rows4_max(rmax);
;                         const float mnew = fmaxf(mrow[rg], rmax); msafe = (mnew == -INFINITY) ? 0.f : mnew;
;                         alpha = __builtin_amdgcn_exp2f(mrow[rg] - msafe); mrow[rg] = mnew;
; #pragma unroll
;                         for (int kb = 0; kb < 4; ++kb)
; #pragma unroll
;                             for (int i = 0; i < 4; ++i) st[rg][kb][i] = __builtin_amdgcn_exp2f(st[rg][kb][i] - msafe);
;                     }
;                     float rs = 0.f;
; #pragma unroll
;                     for (int kb = 0; kb < 4; ++kb) rs += (st[rg][kb][0] + st[rg][kb][1]) + (st[rg][kb][2] + st[rg][kb][3]);
;                     lrow[rg] = lrow[rg] * alpha + rs;
	v_fmac_f32_e32 v3, 0x3e38aa3b, v48
	v_cmp_lt_i32_e32 vcc, -1, v0
	v_fmac_f32_e32 v53, 0x3e38aa3b, v49
	v_fmac_f32_e32 v55, 0x3e38aa3b, v50
	v_cndmask_b32_e32 v3, v221, v3, vcc
	v_cmp_lt_i32_e32 vcc, -1, v52
	v_fmac_f32_e32 v57, 0x3e38aa3b, v51
	s_nop 0
	v_cndmask_b32_e32 v48, v221, v53, vcc
	v_cmp_lt_i32_e32 vcc, -1, v54
	v_max3_f32 v0, v3, s87, v48
	v_mov_b32_e32 v54, v222
	v_cndmask_b32_e32 v50, v221, v55, vcc
	v_cmp_lt_i32_e32 vcc, -1, v56
	s_nop 1
	v_cndmask_b32_e32 v49, v221, v57, vcc
	v_max3_f32 v0, v0, v50, v49
	v_mov_b32_e32 v51, v0
	s_nop 1
	v_permlane16_swap_b32_e32 v0, v51
	v_max_f32_e32 v0, v0, v51
	v_mov_b32_e32 v51, v0
	s_nop 1
	v_permlane32_swap_b32_e32 v0, v51
	v_max3_f32 v0, v0, v51, s87
	v_cmp_neq_f32_e32 vcc, s87, v0
	s_nop 1
	v_cndmask_b32_e32 v51, 0, v0, vcc
	v_sub_f32_e32 v48, v48, v51
	v_sub_f32_e32 v52, v49, v51
	v_exp_f32_e32 v49, v48
	v_sub_f32_e32 v48, 0xff800000, v51
	v_sub_f32_e32 v3, v3, v51
	v_exp_f32_e32 v48, v48
	v_sub_f32_e32 v50, v50, v51
	v_exp_f32_e32 v3, v3
	v_exp_f32_e32 v50, v50
	v_exp_f32_e32 v51, v52
	v_sub_u32_e32 v52, v166, v189
	v_cmp_neq_f32_e32 vcc, 1.0, v48
	v_cmp_gt_u32_e64 s[44:45], s77, v52
	v_cvt_pk_bf16_f32 v68, v48, v48
	v_cvt_pk_bf16_f32 v69, v48, v48
	v_cvt_pk_bf16_f32 v70, v48, v48
	v_cvt_pk_bf16_f32 v71, v48, v48
	v_cvt_pk_bf16_f32 v64, v48, v48
	v_cvt_pk_bf16_f32 v65, v48, v48
	v_cvt_pk_bf16_f32 v66, v3, v49
	v_cvt_pk_bf16_f32 v67, v50, v51
	s_and_saveexec_b64 s[28:29], s[44:45]
	v_lshl_add_u32 v53, v52, 2, 0
	v_add_u32_e32 v53, 0x11800, v53
	ds_read_b32 v54, v53
	s_or_b64 exec, exec, s[28:29]
	v_sub_u32_e32 v56, v166, v190
	v_cmp_gt_u32_e64 s[44:45], s77, v56
	v_mov_b32_e32 v57, v222
	s_and_saveexec_b64 s[28:29], s[44:45]
	v_lshl_add_u32 v53, v56, 2, 0
	v_add_u32_e32 v53, 0x11800, v53
	ds_read_b32 v57, v53
	s_or_b64 exec, exec, s[28:29]
	v_sub_u32_e32 v58, v166, v191
	v_cmp_gt_u32_e64 s[44:45], s77, v58
	v_mov_b32_e32 v59, v222
	s_and_saveexec_b64 s[28:29], s[44:45]
	v_lshl_add_u32 v53, v58, 2, 0
	v_add_u32_e32 v53, 0x11800, v53
	ds_read_b32 v59, v53
	s_or_b64 exec, exec, s[28:29]
	v_sub_u32_e32 v53, v166, v192
	v_cmp_gt_u32_e64 s[44:45], s77, v53
	v_mov_b32_e32 v55, v222
	s_and_saveexec_b64 s[28:29], s[44:45]
	v_lshl_add_u32 v55, v53, 2, 0
	v_add_u32_e32 v55, 0x11800, v55
	ds_read_b32 v55, v55
	s_or_b64 exec, exec, s[28:29]
	s_waitcnt lgkmcnt(0)
	v_fmac_f32_e32 v54, 0x3e38aa3b, v44
	v_cmp_lt_i32_e64 s[44:45], -1, v52
	v_fmac_f32_e32 v59, 0x3e38aa3b, v46
	v_add_f32_e32 v46, v48, v48
	v_cndmask_b32_e64 v44, v221, v54, s[44:45]
	v_cmp_lt_i32_e64 s[44:45], -1, v56
	v_fma_f32 v56, v46, 2.0, 0
	v_fmac_f32_e32 v56, 2.0, v46
	v_fmac_f32_e32 v56, 2.0, v46
	v_add_f32_e32 v3, v3, v49
	v_add_f32_e32 v46, v51, v50
	s_cmp_lg_u64 vcc, 0
	v_fmac_f32_e32 v57, 0x3e38aa3b, v45
	v_add_f32_e32 v3, v3, v46
	v_mul_f32_e32 v46, 0, v48
	s_cselect_b64 vcc, -1, 0
	v_cndmask_b32_e64 v45, v221, v57, s[44:45]
	v_cmp_lt_i32_e64 s[44:45], -1, v58
	v_cndmask_b32_e32 v104, 0, v46, vcc
	v_fmac_f32_e32 v55, 0x3e38aa3b, v47
	v_cmp_lt_i32_e32 vcc, -1, v53
	v_max3_f32 v52, v44, s87, v45
	v_cndmask_b32_e64 v54, v221, v59, s[44:45]
	v_cndmask_b32_e32 v46, v221, v55, vcc
	v_add_f32_e32 v3, v3, v56
	v_max3_f32 v47, v52, v54, v46
	v_fmac_f32_e32 v3, 0, v48
	v_mov_b32_e32 v48, v47
	s_nop 1
	v_permlane16_swap_b32_e32 v47, v48
	v_max_f32_e32 v47, v47, v48
	v_mov_b32_e32 v48, v47
	s_nop 1
	v_permlane32_swap_b32_e32 v47, v48
	v_max3_f32 v199, v47, v48, s87
	v_cmp_neq_f32_e32 vcc, s87, v199
	v_mov_b32_e32 v105, v104
	v_mov_b32_e32 v106, v104
	v_cndmask_b32_e32 v47, 0, v199, vcc
	v_sub_f32_e32 v45, v45, v47
	v_sub_f32_e32 v49, v46, v47
	v_exp_f32_e32 v46, v45
	v_sub_f32_e32 v45, 0xff800000, v47
	v_exp_f32_e32 v56, v45
	v_sub_f32_e32 v44, v44, v47
	v_sub_f32_e32 v45, v54, v47
	v_exp_f32_e32 v44, v44
	v_exp_f32_e32 v48, v45
	v_exp_f32_e32 v50, v49
	v_add_f32_e32 v51, v56, v56
	v_add_f32_e32 v47, v51, v51
	v_fma_f32 v45, v51, 2.0, 0
	v_mov_b32_e32 v49, v51
	v_pk_add_f32 v[52:53], v[44:45], v[46:47]
	v_pk_add_f32 v[54:55], v[50:51], v[48:49]
	v_cmp_neq_f32_e32 vcc, 1.0, v56
	v_pk_add_f32 v[52:53], v[52:53], v[54:55]
	s_cmp_lg_u64 vcc, 0
	v_add_f32_e32 v167, v52, v53
	v_mul_f32_e32 v45, 0, v56
	s_cselect_b64 vcc, -1, 0
	v_fmac_f32_e32 v167, 0, v56
	v_cndmask_b32_e32 v108, 0, v45, vcc
	v_mov_b32_e32 v107, v104
	v_mov_b32_e32 v109, v108
	v_mov_b32_e32 v110, v108
	v_mov_b32_e32 v111, v108
	v_cvt_pk_bf16_f32 v112, v56, v56
	v_cvt_pk_bf16_f32 v113, v56, v56
	v_cvt_pk_bf16_f32 v114, v56, v56
	v_cvt_pk_bf16_f32 v115, v56, v56
	v_cvt_pk_bf16_f32 v116, v56, v56
	v_cvt_pk_bf16_f32 v117, v56, v56
	v_cvt_pk_bf16_f32 v118, v44, v46
	v_cvt_pk_bf16_f32 v119, v48, v50
	v_add_u32_e32 v48, 0x9000, v195
	v_add_u32_e32 v56, 0x9800, v195
	ds_read2_b64 v[44:47], v48 offset0:32 offset1:36
	ds_read2_b64 v[48:51], v48 offset0:40 offset1:44
	ds_read2_b64 v[52:55], v56 offset0:64 offset1:68
	ds_read2_b64 v[60:63], v56 offset0:72 offset1:76
	v_add_u32_e32 v56, 0xa000, v195
	ds_read2_b64 v[72:75], v56 offset0:96 offset1:100
	ds_read2_b64 v[76:79], v56 offset0:104 offset1:108
	v_mfma_f32_16x16x32_bf16 v[56:59], v[40:43], v[68:71], v[104:107]
	v_mfma_f32_16x16x32_bf16 v[40:43], v[40:43], v[112:115], v[108:111]
	v_mfma_f32_16x16x32_bf16 v[88:91], v[36:39], v[64:67], v[56:59]
	v_mfma_f32_16x16x32_bf16 v[40:43], v[36:39], v[116:119], v[40:43]
	v_add_u32_e32 v36, 0xa800, v2
	ds_read2_b64 v[84:87], v36 offset0:128 offset1:132
	ds_read2_b64 v[120:123], v36 offset0:136 offset1:140
	v_add_u32_e32 v36, 0xa800, v196
	ds_read2_b64 v[124:127], v36 offset0:128 offset1:132
	ds_read2_b64 v[128:131], v36 offset0:136 offset1:140
	s_waitcnt lgkmcnt(9)
; #define ATT_VLOAD(dst, k0, nk) _Pragma("unroll") for (int k = 0; k < (nk); ++k) _Pragma("unroll") for (int s = 0; s < 2; ++s) { \
;                     const LAS unsigned char* vp = vb_ + (16 * (k + (k0)) + lq) * VPITCH + (32 * s + 4 * g4) * 2; dst[k][s][0] = *(const LAS u32x2*)vp; dst[k][s][1] = *(const LAS u32x2*)(vp + 32); }
; __device__ __forceinline__ void attn_phase(LAS unsigned char* lds, bf16_t* p5, const bf16_t* vt, const float* relb, const float* dalam, const float* subln, float lam_init, int ocol) {
;     ...
;                 u32x2 vc[3][2][2];
;                 ATT_VLOAD(vc, 1, 3)
;                 __builtin_amdgcn_sched_barrier(0);
;                 ATT_PV(va, 0, 1)
;                 __builtin_amdgcn_sched_barrier(0);
;                 u32x2 vd[2][2][2];
;                 ATT_VLOAD(vd, 4, 2)
;                 __builtin_amdgcn_sched_barrier(0);
;                 ATT_PV(vc, 1, 3)
;                 __builtin_amdgcn_sched_barrier(0);
;                 u32x2 ve[2][2][2];
;                 ATT_VLOAD(ve, 6, 2)
;                 __builtin_amdgcn_sched_barrier(0);
;                 ATT_PV(vd, 4, 2)
;                 __builtin_amdgcn_sched_barrier(0);
;                 ATT_PV(ve, 6, 2)
	v_mfma_f32_16x16x32_bf16 v[36:39], v[44:47], v[68:71], v[104:107]
	v_mfma_f32_16x16x32_bf16 v[44:47], v[44:47], v[112:115], v[108:111]
	s_waitcnt lgkmcnt(8)
	v_mfma_f32_16x16x32_bf16 v[92:95], v[48:51], v[64:67], v[36:39]
	v_mfma_f32_16x16x32_bf16 v[56:59], v[48:51], v[116:119], v[44:47]
	s_waitcnt lgkmcnt(7)
	v_mfma_f32_16x16x32_bf16 v[36:39], v[52:55], v[68:71], v[104:107]
	v_mfma_f32_16x16x32_bf16 v[44:47], v[52:55], v[112:115], v[108:111]
	s_waitcnt lgkmcnt(6)
	v_mfma_f32_16x16x32_bf16 v[80:83], v[60:63], v[64:67], v[36:39]
	v_mfma_f32_16x16x32_bf16 v[48:51], v[60:63], v[116:119], v[44:47]
	s_waitcnt lgkmcnt(5)
	v_mfma_f32_16x16x32_bf16 v[36:39], v[72:75], v[68:71], v[104:107]
	v_mfma_f32_16x16x32_bf16 v[44:47], v[72:75], v[112:115], v[108:111]
	s_waitcnt lgkmcnt(4)
	v_mfma_f32_16x16x32_bf16 v[72:75], v[76:79], v[64:67], v[36:39]
	v_mfma_f32_16x16x32_bf16 v[36:39], v[76:79], v[116:119], v[44:47]
	v_add_u32_e32 v2, 0xb800, v2
	s_nop 3
	ds_read2_b64 v[44:47], v2 offset0:192 offset1:196
	ds_read2_b64 v[132:135], v2 offset0:200 offset1:204
	v_add_u32_e32 v2, 0xb800, v196
	ds_read2_b64 v[136:139], v2 offset0:192 offset1:196
	ds_read2_b64 v[200:203], v2 offset0:200 offset1:204
	s_waitcnt lgkmcnt(7)
	v_mfma_f32_16x16x32_bf16 v[52:55], v[84:87], v[68:71], v[104:107]
	v_mfma_f32_16x16x32_bf16 v[60:63], v[84:87], v[112:115], v[108:111]
	s_waitcnt lgkmcnt(6)
	v_mfma_f32_16x16x32_bf16 v[96:99], v[120:123], v[64:67], v[52:55]
	s_waitcnt lgkmcnt(5)
	v_mfma_f32_16x16x32_bf16 v[52:55], v[124:127], v[68:71], v[104:107]
	v_mfma_f32_16x16x32_bf16 v[76:79], v[124:127], v[112:115], v[108:111]
	v_mfma_f32_16x16x32_bf16 v[60:63], v[120:123], v[116:119], v[60:63]
	s_waitcnt lgkmcnt(4)
	v_mfma_f32_16x16x32_bf16 v[84:87], v[128:131], v[64:67], v[52:55]
	v_mfma_f32_16x16x32_bf16 v[52:55], v[128:131], v[116:119], v[76:79]
	s_waitcnt lgkmcnt(3)
	v_mfma_f32_16x16x32_bf16 v[76:79], v[44:47], v[68:71], v[104:107]
	v_mfma_f32_16x16x32_bf16 v[44:47], v[44:47], v[112:115], v[108:111]
	s_waitcnt lgkmcnt(1)
	v_mfma_f32_16x16x32_bf16 v[68:71], v[136:139], v[68:71], v[104:107]
	v_mfma_f32_16x16x32_bf16 v[104:107], v[136:139], v[112:115], v[108:111]
	v_mfma_f32_16x16x32_bf16 v[76:79], v[132:135], v[64:67], v[76:79]
	v_mfma_f32_16x16x32_bf16 v[44:47], v[132:135], v[116:119], v[44:47]
	s_waitcnt lgkmcnt(0)
	v_mfma_f32_16x16x32_bf16 v[68:71], v[200:203], v[64:67], v[68:71]
	v_mfma_f32_16x16x32_bf16 v[64:67], v[200:203], v[116:119], v[104:107]
	s_branch .LBB0_666

; __device__ __forceinline__ void attn_phase(LAS unsigned char* lds, bf16_t* p5, const bf16_t* vt, const float* relb, const float* dalam, const float* subln, float lam_init, int ocol) {
;     ...
;         for (int j = 0; j < njt; ++j) {
;             if (j + 1 < njt) ATT_LOAD(j + 1);
;             if (j * 64 <= qrow0 + 31) {
;                 const LAS unsigned char* kb_ = lds + (j & 1) * KBYTES; const LAS unsigned char* vb_ = lds + 2 * KBYTES + (j & 1) * VBYTES;
;                 bf16x8 kf[4][2];
; #pragma unroll
;                 for (int kb = 0; kb < 4; ++kb)
; #pragma unroll
;                     for (int s = 0; s < 2; ++s) kf[kb][s] = *(const LAS bf16x8*)(kb_ + (16 * kb + lq) * KPITCH + (cc * 64 + s * 32 + 8 * g4) * 2);
;                 __builtin_amdgcn_sched_barrier(0);
;                 f32x4 st[2][4];
; #pragma unroll
;                 for (int kb = 0; kb < 4; ++kb)
; #pragma unroll
;                     for (int rg = 0; rg < 2; ++rg) { f32x4 a = (f32x4){0.f, 0.f, 0.f, 0.f};
; #pragma unroll
;                         for (int s = 0; s < 2; ++s) a = __builtin_amdgcn_mfma_f32_16x16x32_bf16(kf[kb][s], qf[rg][s], a, 0, 0, 0);
;                         st[rg][kb] = a; }
;                 __builtin_amdgcn_sched_barrier(0);
;     ...
;                 u32x2 va[1][2][2];
;                 ATT_VLOAD(va, 0, 1)
;                 __builtin_amdgcn_sched_barrier(0);
;                 const bool far = (j >= 1) && (j * 64 + 63 + 113 <= qrow0);
;                 bf16x8 pk[2][2];
; #pragma unroll
;                 for (int rg = 0; rg < 2; ++rg) {
;                     float rmax = -INFINITY, msafe, alpha;
;                     if (far) {
; #pragma unroll
;                         for (int kb = 0; kb < 4; ++kb)
; #pragma unroll
;                             for (int i = 0; i < 4; ++i) rmax = fmaxf(rmax, st[rg][kb][i]);
;                         rmax = rows4_max(rmax);
;                         const float mnew = fmaxf(mrow[rg], rmax * sc2 + bfar); msafe = mnew;
;                         alpha = __builtin_amdgcn_exp2f(mrow[rg] - msafe); mrow[rg] = mnew;
;                         const float off = bfar - msafe;
; #pragma unroll
;                         for (int kb = 0; kb < 4; ++kb)
; #pragma unroll
;                             for (int i = 0; i < 4; ++i) st[rg][kb][i] = __builtin_amdgcn_exp2f(st[rg][kb][i] * sc2 + off);
;                     } else {
.LBB0_669:
	s_add_i32 s31, s49, 0xffffff50
	s_cmp_gt_i32 s31, s47
	s_cbranch_scc1 .LBB0_713
	s_and_b32 s30, s30, 1
	s_mul_i32 s31, s30, 0x4400
	v_add3_u32 v2, v175, s31, v186
	ds_read_b128 v[100:103], v2
	ds_read_b128 v[104:107], v2 offset:64
	ds_read_b128 v[108:111], v2 offset:4352
	ds_read_b128 v[112:115], v2 offset:4416
	ds_read_b128 v[124:127], v2 offset:8704
	ds_read_b128 v[200:203], v2 offset:8768
	ds_read_b128 v[204:207], v2 offset:13056
	ds_read_b128 v[224:227], v2 offset:13120
	s_mulk_i32 s30, 0x4800
	s_waitcnt lgkmcnt(7)
	v_mfma_f32_16x16x32_bf16 v[116:119], v[100:103], v[4:7], 0
	s_add_i32 s51, s30, 0
	v_mfma_f32_16x16x32_bf16 v[100:103], v[100:103], v[12:15], 0
	s_waitcnt lgkmcnt(6)
	v_mfma_f32_16x16x32_bf16 v[120:123], v[104:107], v[16:19], v[100:103]
	s_waitcnt lgkmcnt(5)
	v_mfma_f32_16x16x32_bf16 v[100:103], v[108:111], v[4:7], 0
	s_waitcnt lgkmcnt(4)
	v_mfma_f32_16x16x32_bf16 v[132:135], v[112:115], v[8:11], v[100:103]
	v_mfma_f32_16x16x32_bf16 v[100:103], v[108:111], v[12:15], 0
	v_mfma_f32_16x16x32_bf16 v[136:139], v[104:107], v[8:11], v[116:119]
	v_mfma_f32_16x16x32_bf16 v[116:119], v[112:115], v[16:19], v[100:103]
	s_waitcnt lgkmcnt(3)
	v_mfma_f32_16x16x32_bf16 v[100:103], v[124:127], v[4:7], 0
	s_waitcnt lgkmcnt(2)
	v_mfma_f32_16x16x32_bf16 v[128:131], v[200:203], v[8:11], v[100:103]
	v_mfma_f32_16x16x32_bf16 v[100:103], v[124:127], v[12:15], 0
	v_mfma_f32_16x16x32_bf16 v[112:115], v[200:203], v[16:19], v[100:103]
	s_waitcnt lgkmcnt(1)
	v_mfma_f32_16x16x32_bf16 v[100:103], v[204:207], v[4:7], 0
	s_waitcnt lgkmcnt(0)
	v_mfma_f32_16x16x32_bf16 v[124:127], v[224:227], v[8:11], v[100:103]
	v_mfma_f32_16x16x32_bf16 v[100:103], v[204:207], v[12:15], 0
	v_mfma_f32_16x16x32_bf16 v[108:111], v[224:227], v[16:19], v[100:103]
	v_add_u32_e32 v2, s51, v176
	v_add_u32_e32 v200, v2, v140
	v_add_u32_e32 v2, 0x8800, v200
	ds_read2_b64 v[104:107], v2 offset1:4
	s_nop 2
	ds_read2_b64 v[100:103], v2 offset0:8 offset1:12
	s_cmp_le_i32 s49, s46
	s_cselect_b64 s[34:35], -1, 0
	s_cmp_gt_i32 s49, s46
	s_mov_b64 s[30:31], -1
	s_cbranch_scc1 .LBB0_672
	v_max3_f32 v2, v136, s87, v137
	v_max3_f32 v2, v2, v138, v139
	v_max3_f32 v2, v2, v132, v133
	v_max3_f32 v2, v2, v134, v135
	v_max3_f32 v2, v2, v128, v129
	v_max3_f32 v2, v2, v130, v131
	v_max3_f32 v2, v2, v124, v125
	v_max3_f32 v2, v2, v126, v127
	v_mov_b32_e32 v161, v2
	s_nop 1
	v_permlane16_swap_b32_e32 v2, v161
	v_max_f32_e32 v2, v2, v161
	v_mov_b32_e32 v161, v2
	s_nop 1
	v_permlane32_swap_b32_e32 v2, v161
	v_max_f32_e32 v2, v2, v161
	v_fmamk_f32 v2, v2, 0x3e38aa3b, v222
	v_max_f32_e32 v201, v0, v2
	v_sub_f32_e32 v233, v222, v201
	v_fmamk_f32 v2, v136, 0x3e38aa3b, v233
	v_exp_f32_e32 v202, v2
	v_fmamk_f32 v2, v137, 0x3e38aa3b, v233
	v_exp_f32_e32 v203, v2
	v_fmamk_f32 v2, v138, 0x3e38aa3b, v233
	v_exp_f32_e32 v204, v2
	v_fmamk_f32 v2, v139, 0x3e38aa3b, v233
	v_exp_f32_e32 v206, v2
	v_fmamk_f32 v2, v132, 0x3e38aa3b, v233
	v_exp_f32_e32 v205, v2
	v_fmamk_f32 v2, v133, 0x3e38aa3b, v233
	v_exp_f32_e32 v207, v2
	v_fmamk_f32 v2, v134, 0x3e38aa3b, v233
	v_exp_f32_e32 v224, v2
	v_fmamk_f32 v2, v135, 0x3e38aa3b, v233
	v_exp_f32_e32 v226, v2
	v_fmamk_f32 v2, v128, 0x3e38aa3b, v233
	v_exp_f32_e32 v225, v2
	v_fmamk_f32 v2, v129, 0x3e38aa3b, v233
	v_exp_f32_e32 v227, v2
	v_fmamk_f32 v2, v130, 0x3e38aa3b, v233
	v_exp_f32_e32 v228, v2
	v_fmamk_f32 v2, v131, 0x3e38aa3b, v233
	v_exp_f32_e32 v229, v2
	v_fmamk_f32 v2, v124, 0x3e38aa3b, v233
	v_exp_f32_e32 v230, v2
	v_fmamk_f32 v2, v125, 0x3e38aa3b, v233
	v_exp_f32_e32 v231, v2
	v_fmamk_f32 v2, v126, 0x3e38aa3b, v233
	v_exp_f32_e32 v232, v2
	v_fmac_f32_e32 v233, 0x3e38aa3b, v127
	s_mov_b64 s[30:31], 0
.LBB0_672:
	v_add_u32_e32 v2, -16, v198
	s_andn2_b64 vcc, exec, s[30:31]
	v_cmp_gt_u32_e64 s[44:45], s77, v2
	v_mov_b32_e32 v161, v201
	s_cbranch_vccnz .LBB0_706
	v_mov_b32_e32 v201, v222
	s_and_saveexec_b64 s[30:31], s[44:45]
	ds_read_b32 v201, v169 offset:204
	s_or_b64 exec, exec, s[30:31]
	v_subrev_u32_e32 v202, 17, v198
	v_cmp_gt_u32_e32 vcc, s77, v202
	v_mov_b32_e32 v203, v222
	s_and_saveexec_b64 s[30:31], vcc
	ds_read_b32 v203, v169 offset:200
	s_or_b64 exec, exec, s[30:31]
	v_subrev_u32_e32 v204, 18, v198
	v_cmp_gt_u32_e32 vcc, s77, v204
	v_mov_b32_e32 v205, v222
	s_and_saveexec_b64 s[30:31], vcc
	ds_read_b32 v205, v169 offset:196
	s_or_b64 exec, exec, s[30:31]
	v_subrev_u32_e32 v206, 19, v198
	v_cmp_gt_u32_e32 vcc, s77, v206
	v_mov_b32_e32 v207, v222
	s_and_saveexec_b64 s[30:31], vcc
	ds_read_b32 v207, v169 offset:192
	s_or_b64 exec, exec, s[30:31]
	v_subrev_u32_e32 v225, 32, v198
	v_cmp_gt_u32_e32 vcc, s77, v225
	v_mov_b32_e32 v224, v222
	s_and_saveexec_b64 s[30:31], vcc
	ds_read_b32 v224, v169 offset:140
	s_or_b64 exec, exec, s[30:31]
	v_subrev_u32_e32 v227, 33, v198
	v_cmp_gt_u32_e32 vcc, s77, v227
	v_mov_b32_e32 v226, v222
	s_and_saveexec_b64 s[30:31], vcc
	ds_read_b32 v226, v169 offset:136
	s_or_b64 exec, exec, s[30:31]
	v_subrev_u32_e32 v229, 34, v198
	v_cmp_gt_u32_e32 vcc, s77, v229
	v_mov_b32_e32 v228, v222
	s_and_saveexec_b64 s[30:31], vcc
	ds_read_b32 v228, v169 offset:132
	s_or_b64 exec, exec, s[30:31]
	v_subrev_u32_e32 v231, 35, v198
	v_cmp_gt_u32_e32 vcc, s77, v231
	v_mov_b32_e32 v230, v222
	s_and_saveexec_b64 s[30:31], vcc
	ds_read_b32 v230, v169 offset:128
	s_or_b64 exec, exec, s[30:31]
	v_subrev_u32_e32 v233, 48, v198
	v_cmp_gt_u32_e32 vcc, s77, v233
	v_mov_b32_e32 v232, v222
	s_and_saveexec_b64 s[30:31], vcc
	ds_read_b32 v232, v169 offset:76
	s_or_b64 exec, exec, s[30:31]
	v_subrev_u32_e32 v235, 49, v198
	v_cmp_gt_u32_e32 vcc, s77, v235
	v_mov_b32_e32 v234, v222
	s_and_saveexec_b64 s[30:31], vcc
	ds_read_b32 v234, v169 offset:72
	s_or_b64 exec, exec, s[30:31]
	v_subrev_u32_e32 v237, 50, v198
	v_cmp_gt_u32_e32 vcc, s77, v237
	v_mov_b32_e32 v236, v222
	s_and_saveexec_b64 s[30:31], vcc
	ds_read_b32 v236, v169 offset:68
	s_or_b64 exec, exec, s[30:31]
	v_subrev_u32_e32 v239, 51, v198
	v_cmp_gt_u32_e32 vcc, s77, v239
	v_mov_b32_e32 v238, v222
	s_and_saveexec_b64 s[30:31], vcc
	ds_read_b32 v238, v169 offset:64
	s_or_b64 exec, exec, s[30:31]
	v_subrev_u32_e32 v240, 64, v198
	v_cmp_gt_u32_e32 vcc, s77, v240
	v_mov_b32_e32 v241, v222
	s_and_saveexec_b64 s[30:31], vcc
	ds_read_b32 v241, v169 offset:12
	s_or_b64 exec, exec, s[30:31]
	v_add_u32_e32 v242, 0xffffffbf, v198
	v_cmp_gt_u32_e32 vcc, s77, v242
	v_mov_b32_e32 v243, v222
	s_and_saveexec_b64 s[30:31], vcc
	ds_read_b32 v243, v169 offset:8
	s_or_b64 exec, exec, s[30:31]
	v_add_u32_e32 v220, 0xffffffbe, v198
	v_cmp_gt_u32_e32 vcc, s77, v220
	v_mov_b32_e32 v161, v222
	s_and_saveexec_b64 s[30:31], vcc
	ds_read_b32 v161, v169 offset:4
	s_or_b64 exec, exec, s[30:31]
	v_add_u32_e32 v212, 0xffffffbd, v198
	v_cmp_gt_u32_e32 vcc, s77, v212
	v_mov_b32_e32 v214, v222
	s_and_saveexec_b64 s[30:31], vcc
	ds_read_b32 v214, v169
	s_or_b64 exec, exec, s[30:31]
	s_waitcnt lgkmcnt(0)
; __device__ __forceinline__ void attn_phase(LAS unsigned char* lds, bf16_t* p5, const bf16_t* vt, const float* relb, const float* dalam, const float* subln, float lam_init, int ocol) {
;     ...
;                     } else {
;                         const int q = qrow0 + 16 * rg + lq;
; #pragma unroll
;                         for (int kb = 0; kb < 4; ++kb)
; #pragma unroll
;                             for (int i = 0; i < 4; ++i) { float v = st[rg][kb][i] * sc2;
;                                 const int kp = j * 64 + 16 * kb + 4 * g4 + i; const int dist = q - kp;
;                                 const float bv = (dist >= 0 && dist < 128) ? btab[dist] : bfar;
;                                 v = (kp >= PADT && dist >= 0) ? v + bv : -INFINITY;
;                                 st[rg][kb][i] = v; rmax = fmaxf(rmax, v); }
;                         rmax = rows4_max(rmax);
;                         const float mnew = fmaxf(mrow[rg], rmax); msafe = (mnew == -INFINITY) ? 0.f : mnew;
;                         alpha = __builtin_amdgcn_exp2f(mrow[rg] - msafe); mrow[rg] = mnew;
; #pragma unroll
;                         for (int kb = 0; kb < 4; ++kb)
; #pragma unroll
;                             for (int i = 0; i < 4; ++i) st[rg][kb][i] = __builtin_amdgcn_exp2f(st[rg][kb][i] - msafe);
	v_fmac_f32_e32 v201, 0x3e38aa3b, v136
	v_cmp_lt_i32_e32 vcc, -1, v2
	v_fmac_f32_e32 v203, 0x3e38aa3b, v137
	v_fmac_f32_e32 v205, 0x3e38aa3b, v138
	v_cndmask_b32_e32 v136, v221, v201, vcc
	v_cmp_lt_i32_e32 vcc, -1, v202
	v_add_u32_e32 v202, s49, v142
	v_fmac_f32_e32 v207, 0x3e38aa3b, v139
	v_cndmask_b32_e32 v137, v221, v203, vcc
	v_cmp_lt_i32_e32 vcc, -1, v204
	v_add_u32_e32 v203, 0xffffff60, v202
	v_cmp_lt_u32_e64 s[44:45], 47, v203
	v_cndmask_b32_e32 v138, v221, v205, vcc
	v_cmp_lt_i32_e32 vcc, -1, v206
	v_fmac_f32_e32 v224, 0x3e38aa3b, v132
	v_add_u32_e32 v203, 0xffffff61, v202
	v_cndmask_b32_e32 v139, v221, v207, vcc
	v_cmp_lt_i32_e32 vcc, -1, v225
	s_and_b64 vcc, s[44:45], vcc
	v_cmp_lt_u32_e64 s[44:45], 47, v203
	v_cndmask_b32_e32 v132, v221, v224, vcc
	v_cmp_lt_i32_e32 vcc, -1, v227
	v_fmac_f32_e32 v226, 0x3e38aa3b, v133
	s_and_b64 vcc, s[44:45], vcc
	v_add_u32_e32 v203, 0xffffff62, v202
	v_cndmask_b32_e32 v133, v221, v226, vcc
	v_cmp_lt_i32_e32 vcc, -1, v229
	v_cmp_lt_u32_e64 s[44:45], 47, v203
	v_fmac_f32_e32 v228, 0x3e38aa3b, v134
	s_and_b64 vcc, s[44:45], vcc
	v_add_u32_e32 v203, 0xffffff63, v202
	v_cndmask_b32_e32 v134, v221, v228, vcc
	v_cmp_lt_i32_e32 vcc, -1, v231
	v_cmp_lt_u32_e64 s[44:45], 47, v203
	v_fmac_f32_e32 v230, 0x3e38aa3b, v135
	s_and_b64 vcc, s[44:45], vcc
	v_add_u32_e32 v203, 0xffffff70, v202
	v_cndmask_b32_e32 v135, v221, v230, vcc
	v_cmp_lt_i32_e32 vcc, -1, v233
	v_cmp_lt_u32_e64 s[44:45], 47, v203
	v_fmac_f32_e32 v232, 0x3e38aa3b, v128
	s_and_b64 vcc, s[44:45], vcc
	v_add_u32_e32 v203, 0xffffff71, v202
	v_cndmask_b32_e32 v128, v221, v232, vcc
	v_cmp_lt_i32_e32 vcc, -1, v235
	v_cmp_lt_u32_e64 s[44:45], 47, v203
	v_fmac_f32_e32 v234, 0x3e38aa3b, v129
	s_and_b64 vcc, s[44:45], vcc
	v_add_u32_e32 v203, 0xffffff72, v202
	v_cndmask_b32_e32 v129, v221, v234, vcc
	v_cmp_lt_i32_e32 vcc, -1, v237
	v_cmp_lt_u32_e64 s[44:45], 47, v203
	v_fmac_f32_e32 v236, 0x3e38aa3b, v130
	s_and_b64 vcc, s[44:45], vcc
	v_add_u32_e32 v202, 0xffffff73, v202
	v_max3_f32 v201, v136, s87, v137
	v_cndmask_b32_e32 v130, v221, v236, vcc
	v_cmp_lt_i32_e32 vcc, -1, v239
	v_cmp_lt_u32_e64 s[44:45], 47, v202
	v_max3_f32 v201, v201, v138, v139
	v_fmac_f32_e32 v238, 0x3e38aa3b, v131
	s_and_b64 vcc, s[44:45], vcc
	v_max3_f32 v201, v201, v132, v133
	v_cndmask_b32_e32 v131, v221, v238, vcc
	v_fmac_f32_e32 v241, 0x3e38aa3b, v124
	v_cmp_lt_i32_e32 vcc, -1, v240
	v_max3_f32 v201, v201, v134, v135
	v_fmac_f32_e32 v243, 0x3e38aa3b, v125
	v_cndmask_b32_e32 v124, v221, v241, vcc
	v_cmp_lt_i32_e32 vcc, -1, v242
	v_max3_f32 v201, v201, v128, v129
	v_fmac_f32_e32 v161, 0x3e38aa3b, v126
	v_cndmask_b32_e32 v125, v221, v243, vcc
	v_cmp_lt_i32_e32 vcc, -1, v220
	v_max3_f32 v201, v201, v130, v131
	v_fmac_f32_e32 v214, 0x3e38aa3b, v127
	v_cndmask_b32_e32 v126, v221, v161, vcc
	v_cmp_lt_i32_e32 vcc, -1, v212
	v_max3_f32 v201, v201, v124, v125
	s_nop 0
	v_cndmask_b32_e32 v127, v221, v214, vcc
	v_max3_f32 v161, v201, v126, v127
	v_mov_b32_e32 v201, v161
	s_nop 1
	v_permlane16_swap_b32_e32 v161, v201
	v_max_f32_e32 v161, v161, v201
	v_mov_b32_e32 v201, v161
	s_nop 1
	v_permlane32_swap_b32_e32 v161, v201
	v_max3_f32 v201, v0, v161, v201
	v_cmp_neq_f32_e32 vcc, s87, v201
	s_nop 1
	v_cndmask_b32_e32 v161, 0, v201, vcc
	v_sub_f32_e32 v136, v136, v161
	v_sub_f32_e32 v132, v132, v161
	v_sub_f32_e32 v128, v128, v161
	v_exp_f32_e32 v202, v136
	v_sub_f32_e32 v136, v137, v161
	v_exp_f32_e32 v205, v132
	v_sub_f32_e32 v132, v133, v161
	v_exp_f32_e32 v225, v128
	v_sub_f32_e32 v128, v129, v161
	v_sub_f32_e32 v124, v124, v161
	v_exp_f32_e32 v203, v136
	v_sub_f32_e32 v136, v138, v161
	v_exp_f32_e32 v207, v132
	v_sub_f32_e32 v132, v134, v161
	v_exp_f32_e32 v227, v128
	v_sub_f32_e32 v128, v130, v161
	v_exp_f32_e32 v230, v124
	v_sub_f32_e32 v124, v125, v161
	v_exp_f32_e32 v204, v136
	v_sub_f32_e32 v136, v139, v161
	v_exp_f32_e32 v224, v132
	v_sub_f32_e32 v132, v135, v161
	v_exp_f32_e32 v228, v128
	v_sub_f32_e32 v128, v131, v161
	v_exp_f32_e32 v231, v124
	v_sub_f32_e32 v124, v126, v161
	v_exp_f32_e32 v206, v136
	v_exp_f32_e32 v226, v132
	v_exp_f32_e32 v229, v128
	v_exp_f32_e32 v232, v124
	v_sub_f32_e32 v233, v127, v161

; __device__ __forceinline__ unsigned cvt_pk_bf16(float lo, float hi) { unsigned r; asm volatile("v_cvt_pk_bf16_f32 %0, %1, %2" : "=v"(r) : "v"(lo), "v"(hi)); return r; }
; __device__ __forceinline__ void attn_phase(LAS unsigned char* lds, bf16_t* p5, const bf16_t* vt, const float* relb, const float* dalam, const float* subln, float lam_init, int ocol) {
;     ...
;                 for (int rg = 0; rg < 2; ++rg) {
;                     float rmax = -INFINITY, msafe, alpha;
;                     if (far) {
; #pragma unroll
;                         for (int kb = 0; kb < 4; ++kb)
; #pragma unroll
;                             for (int i = 0; i < 4; ++i) rmax = fmaxf(rmax, st[rg][kb][i]);
;                         rmax = rows4_max(rmax);
;                         const float mnew = fmaxf(mrow[rg], rmax * sc2 + bfar); msafe = mnew;
;                         alpha = __builtin_amdgcn_exp2f(mrow[rg] - msafe); mrow[rg] = mnew;
;                         const float off = bfar - msafe;
; #pragma unroll
;                         for (int kb = 0; kb < 4; ++kb)
; #pragma unroll
;                             for (int i = 0; i < 4; ++i) st[rg][kb][i] = __builtin_amdgcn_exp2f(st[rg][kb][i] * sc2 + off);
;     ...
;                     for (int s = 0; s < 2; ++s) { u32x4 w; w.x = cvt_pk_bf16(st[rg][2 * s][0], st[rg][2 * s][1]); w.y = cvt_pk_bf16(st[rg][2 * s][2], st[rg][2 * s][3]);
;                         w.z = cvt_pk_bf16(st[rg][2 * s + 1][0], st[rg][2 * s + 1][1]); w.w = cvt_pk_bf16(st[rg][2 * s + 1][2], st[rg][2 * s + 1][3]);
;                         pk[rg][s] = __builtin_bit_cast(bf16x8, w); }
.LBB0_708:
	v_exp_f32_e32 v132, v233
	s_mov_b64 s[30:31], -1
	s_and_b64 vcc, exec, s[34:35]
	v_cvt_pk_bf16_f32 v124, v202, v203
	v_cvt_pk_bf16_f32 v125, v204, v206
	v_cvt_pk_bf16_f32 v126, v205, v207
	v_cvt_pk_bf16_f32 v127, v224, v226
	v_cvt_pk_bf16_f32 v128, v225, v227
	v_cvt_pk_bf16_f32 v129, v228, v229
	v_cvt_pk_bf16_f32 v130, v230, v231
	v_cvt_pk_bf16_f32 v131, v232, v132
	s_cbranch_vccz .LBB0_717
	v_max3_f32 v133, v120, s87, v121
	v_max3_f32 v133, v133, v122, v123
	v_max3_f32 v133, v133, v116, v117
	v_max3_f32 v133, v133, v118, v119
	v_max3_f32 v133, v133, v112, v113
	v_max3_f32 v133, v133, v114, v115
	v_max3_f32 v133, v133, v108, v109
	v_max3_f32 v133, v133, v110, v111
	v_mov_b32_e32 v134, v133
	s_nop 1
	v_permlane16_swap_b32_e32 v133, v134
	v_max_f32_e32 v133, v133, v134
	v_mov_b32_e32 v134, v133
	s_nop 1
	v_permlane32_swap_b32_e32 v133, v134
	v_max_f32_e32 v133, v133, v134
	v_fmamk_f32 v133, v133, 0x3e38aa3b, v222
	v_max_f32_e32 v133, v199, v133
	v_sub_f32_e32 v242, v222, v133
	v_fmamk_f32 v161, v113, 0x3e38aa3b, v242
	v_exp_f32_e32 v236, v161
	v_fmamk_f32 v161, v114, 0x3e38aa3b, v242
	v_fmamk_f32 v139, v117, 0x3e38aa3b, v242
	v_exp_f32_e32 v235, v161
	v_fmamk_f32 v161, v115, 0x3e38aa3b, v242
	v_exp_f32_e32 v234, v139
	v_fmamk_f32 v139, v118, 0x3e38aa3b, v242
	v_exp_f32_e32 v238, v161
	v_fmamk_f32 v161, v108, 0x3e38aa3b, v242
	v_fmamk_f32 v135, v121, 0x3e38aa3b, v242
	v_fmamk_f32 v137, v123, 0x3e38aa3b, v242
	v_exp_f32_e32 v233, v139
	v_fmamk_f32 v139, v119, 0x3e38aa3b, v242
	v_exp_f32_e32 v239, v161
	v_fmamk_f32 v161, v109, 0x3e38aa3b, v242
	v_fmamk_f32 v134, v120, 0x3e38aa3b, v242
	v_exp_f32_e32 v136, v135
	v_fmamk_f32 v135, v122, 0x3e38aa3b, v242
	v_exp_f32_e32 v138, v137
	v_fmamk_f32 v137, v116, 0x3e38aa3b, v242
	v_exp_f32_e32 v237, v139
	v_fmamk_f32 v139, v112, 0x3e38aa3b, v242
	v_exp_f32_e32 v240, v161
	v_fmamk_f32 v161, v110, 0x3e38aa3b, v242
	v_exp_f32_e32 v134, v134
	v_exp_f32_e32 v135, v135
	v_exp_f32_e32 v137, v137
	v_exp_f32_e32 v139, v139
	v_exp_f32_e32 v241, v161
	v_fmac_f32_e32 v242, 0x3e38aa3b, v111
	v_mov_b32_e32 v161, v133
	s_cbranch_execz .LBB0_718

; __device__ __forceinline__ void attn_phase(LAS unsigned char* lds, bf16_t* p5, const bf16_t* vt, const float* relb, const float* dalam, const float* subln, float lam_init, int ocol) {
;     ...
;                         const int q = qrow0 + 16 * rg + lq;
; #pragma unroll
;                         for (int kb = 0; kb < 4; ++kb)
; #pragma unroll
;                             for (int i = 0; i < 4; ++i) { float v = st[rg][kb][i] * sc2;
;                                 const int kp = j * 64 + 16 * kb + 4 * g4 + i; const int dist = q - kp;
;                                 const float bv = (dist >= 0 && dist < 128) ? btab[dist] : bfar;
;                                 v = (kp >= PADT && dist >= 0) ? v + bv : -INFINITY;
;                                 st[rg][kb][i] = v; rmax = fmaxf(rmax, v); }
.LBB0_718:
	v_cmp_gt_u32_e32 vcc, s77, v198
	v_mov_b32_e32 v133, v222
	s_and_saveexec_b64 s[30:31], vcc
	ds_read_b32 v133, v169 offset:268
	s_or_b64 exec, exec, s[30:31]
	v_add_u32_e32 v134, -1, v198
	v_cmp_gt_u32_e32 vcc, s77, v134
	v_mov_b32_e32 v135, v222
	s_and_saveexec_b64 s[30:31], vcc
	ds_read_b32 v135, v169 offset:264
	s_or_b64 exec, exec, s[30:31]
	v_add_u32_e32 v136, -2, v198
	v_cmp_gt_u32_e32 vcc, s77, v136
	v_mov_b32_e32 v137, v222
	s_and_saveexec_b64 s[30:31], vcc
	ds_read_b32 v137, v169 offset:260
	s_or_b64 exec, exec, s[30:31]
	v_add_u32_e32 v138, -3, v198
	v_cmp_gt_u32_e32 vcc, s77, v138
	v_mov_b32_e32 v139, v222
	s_and_saveexec_b64 s[30:31], vcc
	ds_read_b32 v139, v169 offset:256
	s_or_b64 exec, exec, s[30:31]
	v_cmp_gt_u32_e32 vcc, s77, v2
	v_mov_b32_e32 v233, v222
	s_and_saveexec_b64 s[30:31], vcc
	ds_read_b32 v233, v169 offset:204
	s_or_b64 exec, exec, s[30:31]
	v_subrev_u32_e32 v235, 17, v198
	v_cmp_gt_u32_e32 vcc, s77, v235
	v_mov_b32_e32 v234, v222
	s_and_saveexec_b64 s[30:31], vcc
	ds_read_b32 v234, v169 offset:200
	s_or_b64 exec, exec, s[30:31]
	v_subrev_u32_e32 v237, 18, v198
	v_cmp_gt_u32_e32 vcc, s77, v237
	v_mov_b32_e32 v236, v222
	s_and_saveexec_b64 s[30:31], vcc
	ds_read_b32 v236, v169 offset:196
	s_or_b64 exec, exec, s[30:31]
	v_subrev_u32_e32 v239, 19, v198
	v_cmp_gt_u32_e32 vcc, s77, v239
	v_mov_b32_e32 v238, v222
	s_and_saveexec_b64 s[30:31], vcc
	ds_read_b32 v238, v169 offset:192
	s_or_b64 exec, exec, s[30:31]
	v_subrev_u32_e32 v241, 32, v198
	v_cmp_gt_u32_e32 vcc, s77, v241
	v_mov_b32_e32 v240, v222
	s_and_saveexec_b64 s[30:31], vcc
	ds_read_b32 v240, v169 offset:140
	s_or_b64 exec, exec, s[30:31]
	v_subrev_u32_e32 v243, 33, v198
	v_cmp_gt_u32_e32 vcc, s77, v243
	v_mov_b32_e32 v242, v222
	s_and_saveexec_b64 s[30:31], vcc
	ds_read_b32 v242, v169 offset:136
	s_or_b64 exec, exec, s[30:31]
	v_subrev_u32_e32 v245, 34, v198
	v_cmp_gt_u32_e32 vcc, s77, v245
	v_mov_b32_e32 v244, v222
	s_and_saveexec_b64 s[30:31], vcc
	ds_read_b32 v244, v169 offset:132
	s_or_b64 exec, exec, s[30:31]
	v_subrev_u32_e32 v247, 35, v198
	v_cmp_gt_u32_e32 vcc, s77, v247
	v_mov_b32_e32 v246, v222
	s_and_saveexec_b64 s[30:31], vcc
	ds_read_b32 v246, v169 offset:128
	s_or_b64 exec, exec, s[30:31]
	v_subrev_u32_e32 v248, 48, v198
	v_cmp_gt_u32_e32 vcc, s77, v248
	v_mov_b32_e32 v249, v222
	s_and_saveexec_b64 s[30:31], vcc
	ds_read_b32 v249, v169 offset:76
	s_or_b64 exec, exec, s[30:31]
	v_subrev_u32_e32 v250, 49, v198
	v_cmp_gt_u32_e32 vcc, s77, v250
	v_mov_b32_e32 v251, v222
	s_and_saveexec_b64 s[30:31], vcc
	ds_read_b32 v251, v169 offset:72
	s_or_b64 exec, exec, s[30:31]
	v_subrev_u32_e32 v220, 50, v198
	v_cmp_gt_u32_e32 vcc, s77, v220
	v_mov_b32_e32 v161, v222
	s_and_saveexec_b64 s[30:31], vcc
	ds_read_b32 v161, v169 offset:68
	s_or_b64 exec, exec, s[30:31]
	v_subrev_u32_e32 v212, 51, v198
	v_cmp_gt_u32_e32 vcc, s77, v212
	v_mov_b32_e32 v214, v222
	s_and_saveexec_b64 s[30:31], vcc
	ds_read_b32 v214, v169 offset:64
	s_or_b64 exec, exec, s[30:31]
	s_waitcnt lgkmcnt(0)
; __device__ __forceinline__ void attn_phase(LAS unsigned char* lds, bf16_t* p5, const bf16_t* vt, const float* relb, const float* dalam, const float* subln, float lam_init, int ocol) {
;     ...
;                             for (int i = 0; i < 4; ++i) { float v = st[rg][kb][i] * sc2;
;                                 const int kp = j * 64 + 16 * kb + 4 * g4 + i; const int dist = q - kp;
;                                 const float bv = (dist >= 0 && dist < 128) ? btab[dist] : bfar;
;                                 v = (kp >= PADT && dist >= 0) ? v + bv : -INFINITY;
;                                 st[rg][kb][i] = v; rmax = fmaxf(rmax, v); }
;                         rmax = rows4_max(rmax);
;                         const float mnew = fmaxf(mrow[rg], rmax); msafe = (mnew == -INFINITY) ? 0.f : mnew;
;                         alpha = __builtin_amdgcn_exp2f(mrow[rg] - msafe); mrow[rg] = mnew;
; #pragma unroll
;                         for (int kb = 0; kb < 4; ++kb)
; #pragma unroll
;                             for (int i = 0; i < 4; ++i) st[rg][kb][i] = __builtin_amdgcn_exp2f(st[rg][kb][i] - msafe);
;                     }
;                     float rs = 0.f;
; #pragma unroll
;                     for (int kb = 0; kb < 4; ++kb) rs += (st[rg][kb][0] + st[rg][kb][1]) + (st[rg][kb][2] + st[rg][kb][3]);
;                     lrow[rg] = lrow[rg] * alpha + rs;
;                     if (__builtin_amdgcn_ballot_w64(alpha != 1.0f) != 0ull) {
; #pragma unroll
;                         for (int k = 0; k < 8; ++k) O[rg][k] *= alpha; }
	v_fmac_f32_e32 v133, 0x3e38aa3b, v120
	v_cmp_lt_i32_e32 vcc, -1, v198
	v_fmac_f32_e32 v135, 0x3e38aa3b, v121
	v_fmac_f32_e32 v137, 0x3e38aa3b, v122
	v_cndmask_b32_e32 v120, v221, v133, vcc
	v_cmp_lt_i32_e32 vcc, -1, v134
	s_add_i32 s30, s49, 0xffffff60
	v_fmac_f32_e32 v139, 0x3e38aa3b, v123
	v_cndmask_b32_e32 v121, v221, v135, vcc
	v_cmp_lt_i32_e32 vcc, -1, v136
	s_cmp_gt_u32 s30, 47
	s_cselect_b64 s[30:31], -1, 0
	v_cndmask_b32_e32 v122, v221, v137, vcc
	v_cmp_lt_i32_e32 vcc, -1, v138
	v_fmac_f32_e32 v233, 0x3e38aa3b, v116
	v_add_u32_e32 v116, s49, v142
	v_cndmask_b32_e32 v123, v221, v139, vcc
	v_cmp_lt_i32_e32 vcc, -1, v2
	s_and_b64 vcc, s[30:31], vcc
	v_add_u32_e32 v134, 0xffffff61, v116
	v_cndmask_b32_e32 v2, v221, v233, vcc
	v_cmp_lt_i32_e32 vcc, -1, v235
	v_cmp_lt_u32_e64 s[44:45], 47, v134
	v_fmac_f32_e32 v234, 0x3e38aa3b, v117
	s_and_b64 vcc, s[44:45], vcc
	v_add_u32_e32 v134, 0xffffff62, v116
	v_cndmask_b32_e32 v117, v221, v234, vcc
	v_cmp_lt_i32_e32 vcc, -1, v237
	v_cmp_lt_u32_e64 s[44:45], 47, v134
	v_fmac_f32_e32 v236, 0x3e38aa3b, v118
	s_and_b64 vcc, s[44:45], vcc
	v_add_u32_e32 v134, 0xffffff63, v116
	v_cndmask_b32_e32 v118, v221, v236, vcc
	v_cmp_lt_i32_e32 vcc, -1, v239
	v_cmp_lt_u32_e64 s[44:45], 47, v134
	v_fmac_f32_e32 v238, 0x3e38aa3b, v119
	s_and_b64 vcc, s[44:45], vcc
	v_add_u32_e32 v134, 0xffffff70, v116
	v_cndmask_b32_e32 v119, v221, v238, vcc
	v_cmp_lt_i32_e32 vcc, -1, v241
	v_cmp_lt_u32_e64 s[44:45], 47, v134
	v_fmac_f32_e32 v240, 0x3e38aa3b, v112
	s_and_b64 vcc, s[44:45], vcc
	v_add_u32_e32 v134, 0xffffff71, v116
	v_cndmask_b32_e32 v112, v221, v240, vcc
	v_cmp_lt_i32_e32 vcc, -1, v243
	v_cmp_lt_u32_e64 s[44:45], 47, v134
	v_fmac_f32_e32 v242, 0x3e38aa3b, v113
	s_and_b64 vcc, s[44:45], vcc
	v_add_u32_e32 v134, 0xffffff72, v116
	v_cndmask_b32_e32 v113, v221, v242, vcc
	v_cmp_lt_i32_e32 vcc, -1, v245
	v_cmp_lt_u32_e64 s[44:45], 47, v134
	v_fmac_f32_e32 v244, 0x3e38aa3b, v114
	s_and_b64 vcc, s[44:45], vcc
	v_add_u32_e32 v116, 0xffffff73, v116
	v_max3_f32 v133, v120, s87, v121
	v_cndmask_b32_e32 v114, v221, v244, vcc
	v_cmp_lt_i32_e32 vcc, -1, v247
	v_cmp_lt_u32_e64 s[44:45], 47, v116
	v_max3_f32 v133, v133, v122, v123
	v_fmac_f32_e32 v246, 0x3e38aa3b, v115
	s_and_b64 vcc, s[44:45], vcc
	v_max3_f32 v133, v133, v2, v117
	v_cndmask_b32_e32 v115, v221, v246, vcc
	v_fmac_f32_e32 v249, 0x3e38aa3b, v108
	v_cmp_lt_i32_e32 vcc, -1, v248
	v_max3_f32 v133, v133, v118, v119
	v_fmac_f32_e32 v251, 0x3e38aa3b, v109
	v_cndmask_b32_e32 v108, v221, v249, vcc
	v_cmp_lt_i32_e32 vcc, -1, v250
	v_max3_f32 v133, v133, v112, v113
	v_fmac_f32_e32 v161, 0x3e38aa3b, v110
	v_cndmask_b32_e32 v109, v221, v251, vcc
	v_cmp_lt_i32_e32 vcc, -1, v220
	v_max3_f32 v116, v133, v114, v115
	v_fmac_f32_e32 v214, 0x3e38aa3b, v111
	v_cndmask_b32_e32 v110, v221, v161, vcc
	v_cmp_lt_i32_e32 vcc, -1, v212
	v_max3_f32 v116, v116, v108, v109
	s_nop 0
	v_cndmask_b32_e32 v111, v221, v214, vcc
	v_max3_f32 v116, v116, v110, v111
	v_mov_b32_e32 v133, v116
	s_nop 1
	v_permlane16_swap_b32_e32 v116, v133
	v_max_f32_e32 v116, v116, v133
	v_mov_b32_e32 v133, v116
	s_nop 1
	v_permlane32_swap_b32_e32 v116, v133
	v_max3_f32 v133, v199, v116, v133
	v_cmp_neq_f32_e32 vcc, s87, v133
	s_nop 1
	v_cndmask_b32_e32 v161, 0, v133, vcc
	v_sub_f32_e32 v2, v2, v161
	v_exp_f32_e32 v137, v2
	v_sub_f32_e32 v2, v117, v161
	v_exp_f32_e32 v234, v2
	v_sub_f32_e32 v2, v118, v161
	v_exp_f32_e32 v233, v2
	v_sub_f32_e32 v2, v119, v161
	v_exp_f32_e32 v237, v2
	v_sub_f32_e32 v2, v112, v161
	v_exp_f32_e32 v139, v2
	v_sub_f32_e32 v2, v113, v161
	v_exp_f32_e32 v236, v2
	v_sub_f32_e32 v2, v114, v161
	v_sub_f32_e32 v116, v120, v161
	v_exp_f32_e32 v235, v2
	v_sub_f32_e32 v2, v115, v161
	v_exp_f32_e32 v134, v116
	v_sub_f32_e32 v116, v121, v161
	v_exp_f32_e32 v238, v2
	v_sub_f32_e32 v2, v108, v161
	v_exp_f32_e32 v136, v116
	v_sub_f32_e32 v116, v122, v161
	v_exp_f32_e32 v239, v2
	v_sub_f32_e32 v2, v109, v161
	v_exp_f32_e32 v135, v116
	v_sub_f32_e32 v116, v123, v161
	v_exp_f32_e32 v240, v2
	v_sub_f32_e32 v2, v110, v161
	v_exp_f32_e32 v138, v116
	v_exp_f32_e32 v241, v2
	v_sub_f32_e32 v242, v111, v161
	v_sub_f32_e32 v2, v199, v161
	v_exp_f32_e32 v2, v2
	s_nop 0
	v_cmp_neq_f32_e32 vcc, 1.0, v2
	s_cbranch_vccnz .LBB0_711
	s_branch .LBB0_712
